# residual epilogue: per-row-group sum of squares with packed f32 ops (1 pk_mul + 7 pk_fma + 1 add per group)
# speedup vs baseline: 1.0006x; 1.0006x over previous
; __device__ __forceinline__ void epi_all_run(const void* Pk_, int l, int s, const f32x4 (&acc)[2][2][4][2], const pg8::Unit& u, int wr, int wc, int fr, int fq) {
;     ...
;         } else {
;             const float* MOD = (const float*)(ws + WS_MOD);
;             const int gidx = (s == 1) ? 2 : (s == 4 ? 5 : 8);
;             const float* base = (l == 0 && s == 1) ? A.x : A.out; float* out = A.out;
;             const float* gp = MOD + (size_t)(l * 4 + b) * NMODC + gidx * DM; const float scale = (s == 4) ? 1.0f : 0.5f;
;             const int nsite = 3 * l + (s == 1 ? 1 : (s == 4 ? 2 : 3));
;             const int col0 = u.pn * 256 + wc * 32 + 8 * fq;
;             float* slots = (float*)(ws + WS_RSP) + (size_t)nsite * M * 16;
;             f32x4 gv[2][2];
; #pragma unroll
;             for (int bj = 0; bj < 2; ++bj)
; #pragma unroll
;                 for (int n = 0; n < 2; ++n) gv[bj][n] = *(const f32x4*)(gp + col0 + bj * 128 + n * 4) * scale;
;             f32x4 bb[2][2][2];
; #pragma unroll
;             for (int bj = 0; bj < 2; ++bj)
; #pragma unroll
;                 for (int n = 0; n < 2; ++n) bb[0][bj][n] = *(const f32x4*)(base + (size_t)row0 * DM + col0 + bj * 128 + n * 4);
; #pragma unroll
;             for (int g = 0; g < 8; ++g) {
;                 const int ai = g >> 2, m = g & 3, row = row0 + ai * 128 + m * 16;
;                 if (g < 7) { const int rown = row0 + ((g + 1) >> 2) * 128 + ((g + 1) & 3) * 16;
; #pragma unroll
;                     for (int bj = 0; bj < 2; ++bj)
; #pragma unroll
;                         for (int n = 0; n < 2; ++n) bb[(g + 1) & 1][bj][n] = *(const f32x4*)(base + (size_t)rown * DM + col0 + bj * 128 + n * 4); }
;                 float ss = 0.f;
; #pragma unroll
;                 for (int bj = 0; bj < 2; ++bj)
; #pragma unroll
;                     for (int n = 0; n < 2; ++n) {
;                         const f32x4 h = bb[g & 1][bj][n] + gv[bj][n] * acc[ai][bj][m][n];
;                         *(f32x4*)(out + (size_t)row * DM + col0 + bj * 128 + n * 4) = h;
;                         ss += (h[0] * h[0] + h[1] * h[1]) + (h[2] * h[2] + h[3] * h[3]);
;                     }
;                 if (nsite < 3 * DEPTH) {
;                     ss += shx(ss, 16); ss += shx(ss, 32);
;                     if (fq == 0) __hip_atomic_store(slots + ((size_t)u.pn * M + row) * 4 + wc, ss, __ATOMIC_RELAXED, __HIP_MEMORY_SCOPE_AGENT);
.LBB0_90:
	s_andn2_b64 vcc, exec, s[46:47]
	v_or_b32_e32 v186, 16, v184
	s_cbranch_vccnz .LBB0_125
	s_ashr_i32 s20, s31, 4
	s_cmp_eq_u32 s75, 0
	s_cselect_b64 s[38:39], -1, 0
	s_cmp_eq_u32 s76, 4
	s_cselect_b64 s[46:47], -1, 0
	v_cndmask_b32_e64 v168, 0.5, 1.0, s[46:47]
	s_and_b64 s[46:47], s[46:47], exec
	s_cselect_b32 s31, s93, 0x2000
	s_cselect_b32 s50, 2, 3
	s_cmp_eq_u32 s76, 1
	s_cselect_b64 s[46:47], -1, 0
	s_and_b64 s[48:49], s[46:47], exec
	s_cselect_b32 s31, 0x800, s31
	s_cselect_b32 s48, 1, s50
	s_and_b64 s[38:39], s[38:39], s[46:47]
	s_and_b64 s[38:39], s[38:39], exec
	s_cselect_b32 s38, 0, 0xc0
	s_add_u32 s38, s4, s38
	s_addc_u32 s39, s5, 0
	s_lshl_b32 s46, s75, 2
	s_add_i32 s20, s46, s20
	s_mul_hi_i32 s46, s20, 0x9000
	s_mul_i32 s20, s20, 0x9000
	s_waitcnt lgkmcnt(0)
	s_add_u32 s20, s34, s20
	s_addc_u32 s47, s35, s46
	s_lshl_b32 s31, s31, 2
	v_lshl_or_b32 v130, s30, 8, v228
	s_add_u32 s46, s20, s31
	v_ashrrev_i32_e32 v131, 31, v130
	s_load_dwordx2 s[38:39], s[38:39], 0x0
	s_nop 0
	s_load_dwordx2 s[4:5], s[4:5], 0xc0
	s_addc_u32 s47, s47, 0
	v_lshlrev_b64 v[188:189], 2, v[130:131]
	v_lshl_add_u64 v[130:131], s[46:47], 0, v[188:189]
	s_mov_b64 s[46:47], 0x10000
	s_mov_b32 s20, 0x10000
	v_lshl_add_u64 v[132:133], v[130:131], 0, s[46:47]
	v_add_co_u32_e32 v130, vcc, s20, v130
	v_ashrrev_i32_e32 v185, 31, v184
	s_nop 0
	v_addc_co_u32_e32 v131, vcc, 0, v131, vcc
	v_lshlrev_b64 v[190:191], 12, v[184:185]
	v_ashrrev_i32_e32 v187, 31, v186
	global_load_dwordx4 v[142:145], v[130:131], off
	global_load_dwordx4 v[150:153], v[132:133], off offset:528
	global_load_dwordx4 v[154:157], v[132:133], off offset:16
	global_load_dwordx4 v[158:161], v[132:133], off offset:512
	s_waitcnt lgkmcnt(0)
	v_lshl_add_u64 v[130:131], s[38:39], 0, v[190:191]
	v_lshl_add_u64 v[206:207], s[38:39], 0, v[188:189]
	v_lshlrev_b64 v[166:167], 12, v[186:187]
	v_lshl_add_u64 v[130:131], v[130:131], 0, v[188:189]
	v_lshl_add_u64 v[134:135], v[206:207], 0, v[166:167]
	global_load_dwordx4 v[162:165], v[130:131], off
	global_load_dwordx4 v[208:211], v[130:131], off offset:16
	global_load_dwordx4 v[212:215], v[130:131], off offset:528
	global_load_dwordx4 v[230:233], v[130:131], off offset:512
	global_load_dwordx4 v[138:141], v[134:135], off offset:16
	global_load_dwordx4 v[146:149], v[134:135], off
	s_nop 0
	global_load_dwordx4 v[130:133], v[134:135], off offset:528
	s_nop 0
	global_load_dwordx4 v[134:137], v[134:135], off offset:512
	s_mul_i32 s75, s75, 3
	s_add_i32 s48, s48, s75
	s_ashr_i32 s49, s48, 31
	v_lshl_add_u64 v[200:201], s[4:5], 0, v[188:189]
	s_lshl_b64 s[4:5], s[48:49], 20
	s_add_u32 s4, s34, s4
	s_addc_u32 s5, s35, s5
	s_add_u32 s20, s4, 0xed00000
	s_addc_u32 s46, s5, 0
	v_lshl_add_u64 v[234:235], v[200:201], 0, v[190:191]
	s_cmp_lt_i32 s48, 6
	s_cselect_b64 s[38:39], -1, 0
	s_cmp_gt_i32 s48, 5
	s_waitcnt vmcnt(0)
	v_pk_mul_f32 v[202:203], v[168:169], v[144:145] op_sel_hi:[0,1]
	v_pk_mul_f32 v[204:205], v[168:169], v[142:143] op_sel_hi:[0,1]
	v_pk_mul_f32 v[198:199], v[168:169], v[156:157] op_sel_hi:[0,1]
	v_pk_mul_f32 v[196:197], v[168:169], v[154:155] op_sel_hi:[0,1]
	v_pk_mul_f32 v[192:193], v[168:169], v[160:161] op_sel_hi:[0,1]
	v_pk_mul_f32 v[194:195], v[168:169], v[158:159] op_sel_hi:[0,1]
	v_pk_mul_f32 v[190:191], v[168:169], v[152:153] op_sel_hi:[0,1]
	v_pk_mul_f32 v[188:189], v[168:169], v[150:151] op_sel_hi:[0,1]
	v_pk_fma_f32 v[128:129], v[128:129], v[202:203], v[164:165]
	v_pk_fma_f32 v[126:127], v[126:127], v[204:205], v[162:163]
	v_pk_fma_f32 v[124:125], v[124:125], v[198:199], v[210:211]
	v_pk_fma_f32 v[122:123], v[122:123], v[196:197], v[208:209]
	v_pk_fma_f32 v[120:121], v[120:121], v[192:193], v[232:233]
	v_pk_fma_f32 v[118:119], v[118:119], v[194:195], v[230:231]
	v_pk_fma_f32 v[116:117], v[116:117], v[190:191], v[214:215]
	v_pk_fma_f32 v[114:115], v[114:115], v[188:189], v[212:213]
	global_store_dwordx4 v[234:235], v[126:129], off
	global_store_dwordx4 v[234:235], v[122:125], off offset:16
	global_store_dwordx4 v[234:235], v[118:121], off offset:512
	global_store_dwordx4 v[234:235], v[114:117], off offset:528
	s_cbranch_scc1 .LBB0_95
	v_pk_mul_f32 v[142:143], v[114:115], v[114:115]
	v_pk_fma_f32 v[142:143], v[116:117], v[116:117], v[142:143]
	v_pk_fma_f32 v[142:143], v[118:119], v[118:119], v[142:143]
	v_pk_fma_f32 v[142:143], v[120:121], v[120:121], v[142:143]
	v_pk_fma_f32 v[142:143], v[122:123], v[122:123], v[142:143]
	v_pk_fma_f32 v[142:143], v[124:125], v[124:125], v[142:143]
	v_pk_fma_f32 v[142:143], v[126:127], v[126:127], v[142:143]
	v_pk_fma_f32 v[142:143], v[128:129], v[128:129], v[142:143]
	v_add_f32_e32 v142, v142, v143
	v_mov_b32_e32 v143, v179
	s_nop 0
	v_lshlrev_b32_e32 v143, 2, v143
	v_bitop3_b32 v143, v143, 64, v220 bitop3:0x6c
	ds_bpermute_b32 v143, v143, v142
	s_waitcnt lgkmcnt(0)
	v_add_f32_e32 v142, v142, v143
	v_mov_b32_e32 v143, v179
	s_nop 0
	v_lshlrev_b32_e32 v143, 2, v143
	v_bitop3_b32 v143, v143, s33, v220 bitop3:0x6c
	ds_bpermute_b32 v143, v143, v142
	s_and_saveexec_b64 s[4:5], s[42:43]
	s_cbranch_execz .LBB0_94
	s_ashr_i32 s31, s30, 31
	s_lshl_b64 s[48:49], s[30:31], 18
	s_add_u32 s48, s20, s48
	s_addc_u32 s49, s46, s49
	s_waitcnt lgkmcnt(0)
	v_add_f32_e32 v144, v142, v143
	v_lshl_add_u64 v[142:143], v[184:185], 4, s[48:49]
	v_readlane_b32 s48, v237, 58
	v_readlane_b32 s49, v237, 59
	s_lshl_b32 s48, s64, 2
	s_mov_b32 s31, s49
	v_writelane_b32 v237, s30, 58
	v_lshl_add_u64 v[142:143], v[142:143], 0, s[48:49]
	global_store_dword v[142:143], v144, off sc1
	v_writelane_b32 v237, s31, 59

; __device__ __forceinline__ float shx(float v, int o) { const int idx = (((int)otid() & 63) ^ o) << 2; return __builtin_bit_cast(float, __builtin_amdgcn_ds_bpermute(idx, __builtin_bit_cast(int, v))); }
; __device__ __forceinline__ void epi_all_run(const void* Pk_, int l, int s, const f32x4 (&acc)[2][2][4][2], const pg8::Unit& u, int wr, int wc, int fr, int fq) {
;     ...
;             for (int g = 0; g < 8; ++g) {
;                 const int ai = g >> 2, m = g & 3, row = row0 + ai * 128 + m * 16;
;                 if (g < 7) { const int rown = row0 + ((g + 1) >> 2) * 128 + ((g + 1) & 3) * 16;
; #pragma unroll
;                     for (int bj = 0; bj < 2; ++bj)
; #pragma unroll
;                         for (int n = 0; n < 2; ++n) bb[(g + 1) & 1][bj][n] = *(const f32x4*)(base + (size_t)rown * DM + col0 + bj * 128 + n * 4); }
;                 float ss = 0.f;
; #pragma unroll
;                 for (int bj = 0; bj < 2; ++bj)
; #pragma unroll
;                     for (int n = 0; n < 2; ++n) {
;                         const f32x4 h = bb[g & 1][bj][n] + gv[bj][n] * acc[ai][bj][m][n];
;                         *(f32x4*)(out + (size_t)row * DM + col0 + bj * 128 + n * 4) = h;
;                         ss += (h[0] * h[0] + h[1] * h[1]) + (h[2] * h[2] + h[3] * h[3]);
;                     }
;                 if (nsite < 3 * DEPTH) {
;                     ss += shx(ss, 16); ss += shx(ss, 32);
;                     if (fq == 0) __hip_atomic_store(slots + ((size_t)u.pn * M + row) * 4 + wc, ss, __ATOMIC_RELAXED, __HIP_MEMORY_SCOPE_AGENT);
;                 }
;             }
.LBB0_95:
	v_or_b32_e32 v208, 32, v184
	v_ashrrev_i32_e32 v209, 31, v208
	v_lshlrev_b64 v[212:213], 12, v[208:209]
	v_lshl_add_u64 v[150:151], v[206:207], 0, v[212:213]
	global_load_dwordx4 v[154:157], v[150:151], off offset:16
	global_load_dwordx4 v[162:165], v[150:151], off
	s_waitcnt lgkmcnt(0)
	global_load_dwordx4 v[142:145], v[150:151], off offset:528
	s_nop 0
	global_load_dwordx4 v[150:153], v[150:151], off offset:512
	v_cndmask_b32_e64 v160, 0, 1, s[38:39]
	v_lshl_add_u64 v[158:159], v[200:201], 0, v[166:167]
	v_pk_fma_f32 v[112:113], v[112:113], v[202:203], v[148:149]
	v_pk_fma_f32 v[110:111], v[110:111], v[204:205], v[146:147]
	v_pk_fma_f32 v[108:109], v[108:109], v[198:199], v[140:141]
	v_pk_fma_f32 v[106:107], v[106:107], v[196:197], v[138:139]
	v_pk_fma_f32 v[104:105], v[104:105], v[192:193], v[136:137]
	v_pk_fma_f32 v[102:103], v[102:103], v[194:195], v[134:135]
	v_pk_fma_f32 v[100:101], v[100:101], v[190:191], v[132:133]
	v_pk_fma_f32 v[98:99], v[98:99], v[188:189], v[130:131]
	v_cmp_ne_u32_e64 s[4:5], 1, v160
	s_andn2_b64 vcc, exec, s[38:39]
	global_store_dwordx4 v[158:159], v[110:113], off
	global_store_dwordx4 v[158:159], v[106:109], off offset:16
	global_store_dwordx4 v[158:159], v[102:105], off offset:512
	global_store_dwordx4 v[158:159], v[98:101], off offset:528
	s_cbranch_vccnz .LBB0_99
	v_pk_mul_f32 v[130:131], v[98:99], v[98:99]
	v_pk_fma_f32 v[130:131], v[100:101], v[100:101], v[130:131]
	v_pk_fma_f32 v[130:131], v[102:103], v[102:103], v[130:131]
	v_pk_fma_f32 v[130:131], v[104:105], v[104:105], v[130:131]
	v_pk_fma_f32 v[130:131], v[106:107], v[106:107], v[130:131]
	v_pk_fma_f32 v[130:131], v[108:109], v[108:109], v[130:131]
	v_pk_fma_f32 v[130:131], v[110:111], v[110:111], v[130:131]
	v_pk_fma_f32 v[130:131], v[112:113], v[112:113], v[130:131]
	v_add_f32_e32 v130, v130, v131
	v_mov_b32_e32 v131, v179
	v_lshlrev_b32_e32 v131, 2, v131
	v_bitop3_b32 v131, v131, 64, v220 bitop3:0x6c
	ds_bpermute_b32 v131, v131, v130
	s_waitcnt lgkmcnt(0)
	v_add_f32_e32 v130, v130, v131
	v_mov_b32_e32 v131, v179
	s_nop 0
	v_lshlrev_b32_e32 v131, 2, v131
	v_bitop3_b32 v131, v131, s33, v220 bitop3:0x6c
	ds_bpermute_b32 v131, v131, v130
	s_and_saveexec_b64 s[38:39], s[42:43]
	s_cbranch_execz .LBB0_98
	s_ashr_i32 s31, s30, 31
	s_lshl_b64 s[48:49], s[30:31], 18
	s_add_u32 s48, s20, s48
	s_addc_u32 s49, s46, s49
	s_waitcnt lgkmcnt(0)
	v_add_f32_e32 v132, v130, v131
	v_lshl_add_u64 v[130:131], v[186:187], 4, s[48:49]
	v_readlane_b32 s48, v237, 58
	v_readlane_b32 s49, v237, 59
	s_lshl_b32 s48, s64, 2
	s_mov_b32 s31, s49
	v_writelane_b32 v237, s30, 58
	v_lshl_add_u64 v[130:131], v[130:131], 0, s[48:49]
	global_store_dword v[130:131], v132, off sc1
	v_writelane_b32 v237, s31, 59

; __device__ __forceinline__ float shx(float v, int o) { const int idx = (((int)otid() & 63) ^ o) << 2; return __builtin_bit_cast(float, __builtin_amdgcn_ds_bpermute(idx, __builtin_bit_cast(int, v))); }
; __device__ __forceinline__ void epi_all_run(const void* Pk_, int l, int s, const f32x4 (&acc)[2][2][4][2], const pg8::Unit& u, int wr, int wc, int fr, int fq) {
;     ...
;             for (int g = 0; g < 8; ++g) {
;                 const int ai = g >> 2, m = g & 3, row = row0 + ai * 128 + m * 16;
;                 if (g < 7) { const int rown = row0 + ((g + 1) >> 2) * 128 + ((g + 1) & 3) * 16;
; #pragma unroll
;                     for (int bj = 0; bj < 2; ++bj)
; #pragma unroll
;                         for (int n = 0; n < 2; ++n) bb[(g + 1) & 1][bj][n] = *(const f32x4*)(base + (size_t)rown * DM + col0 + bj * 128 + n * 4); }
;                 float ss = 0.f;
; #pragma unroll
;                 for (int bj = 0; bj < 2; ++bj)
; #pragma unroll
;                     for (int n = 0; n < 2; ++n) {
;                         const f32x4 h = bb[g & 1][bj][n] + gv[bj][n] * acc[ai][bj][m][n];
;                         *(f32x4*)(out + (size_t)row * DM + col0 + bj * 128 + n * 4) = h;
;                         ss += (h[0] * h[0] + h[1] * h[1]) + (h[2] * h[2] + h[3] * h[3]);
;                     }
;                 if (nsite < 3 * DEPTH) {
;                     ss += shx(ss, 16); ss += shx(ss, 32);
;                     if (fq == 0) __hip_atomic_store(slots + ((size_t)u.pn * M + row) * 4 + wc, ss, __ATOMIC_RELAXED, __HIP_MEMORY_SCOPE_AGENT);
;                 }
;             }
.LBB0_99:
	v_or_b32_e32 v210, 48, v184
	v_ashrrev_i32_e32 v211, 31, v210
	v_lshlrev_b64 v[214:215], 12, v[210:211]
	v_lshl_add_u64 v[134:135], v[206:207], 0, v[214:215]
	global_load_dwordx4 v[158:161], v[134:135], off offset:16
	global_load_dwordx4 v[166:169], v[134:135], off
	s_waitcnt lgkmcnt(0)
	global_load_dwordx4 v[130:133], v[134:135], off offset:528
	global_load_dwordx4 v[146:149], v[134:135], off offset:512
	v_lshl_add_u64 v[212:213], v[200:201], 0, v[212:213]
	s_waitcnt vmcnt(10)
	v_pk_fma_f32 v[96:97], v[96:97], v[202:203], v[164:165]
	v_pk_fma_f32 v[94:95], v[94:95], v[204:205], v[162:163]
	v_pk_fma_f32 v[92:93], v[92:93], v[198:199], v[156:157]
	v_pk_fma_f32 v[90:91], v[90:91], v[196:197], v[154:155]
	s_waitcnt vmcnt(8)
	v_pk_fma_f32 v[88:89], v[88:89], v[192:193], v[152:153]
	v_pk_fma_f32 v[86:87], v[86:87], v[194:195], v[150:151]
	v_pk_fma_f32 v[84:85], v[84:85], v[190:191], v[144:145]
	v_pk_fma_f32 v[82:83], v[82:83], v[188:189], v[142:143]
	s_and_b64 vcc, exec, s[4:5]
	global_store_dwordx4 v[212:213], v[94:97], off
	global_store_dwordx4 v[212:213], v[90:93], off offset:16
	global_store_dwordx4 v[212:213], v[86:89], off offset:512
	global_store_dwordx4 v[212:213], v[82:85], off offset:528
	s_cbranch_vccnz .LBB0_103
	v_pk_mul_f32 v[134:135], v[82:83], v[82:83]
	v_pk_fma_f32 v[134:135], v[84:85], v[84:85], v[134:135]
	v_pk_fma_f32 v[134:135], v[86:87], v[86:87], v[134:135]
	v_pk_fma_f32 v[134:135], v[88:89], v[88:89], v[134:135]
	v_pk_fma_f32 v[134:135], v[90:91], v[90:91], v[134:135]
	v_pk_fma_f32 v[134:135], v[92:93], v[92:93], v[134:135]
	v_pk_fma_f32 v[134:135], v[94:95], v[94:95], v[134:135]
	v_pk_fma_f32 v[134:135], v[96:97], v[96:97], v[134:135]
	v_add_f32_e32 v134, v134, v135
	v_mov_b32_e32 v135, v179
	s_nop 0
	v_lshlrev_b32_e32 v135, 2, v135
	v_bitop3_b32 v135, v135, 64, v220 bitop3:0x6c
	ds_bpermute_b32 v135, v135, v134
	s_waitcnt lgkmcnt(0)
	v_add_f32_e32 v134, v134, v135
	v_mov_b32_e32 v135, v179
	s_nop 0
	v_lshlrev_b32_e32 v135, 2, v135
	v_bitop3_b32 v135, v135, s33, v220 bitop3:0x6c
	ds_bpermute_b32 v135, v135, v134
	s_and_saveexec_b64 s[38:39], s[42:43]
	s_cbranch_execz .LBB0_102
	s_ashr_i32 s31, s30, 31
	s_lshl_b64 s[48:49], s[30:31], 18
	s_add_u32 s48, s20, s48
	s_addc_u32 s49, s46, s49
	s_waitcnt lgkmcnt(0)
	v_add_f32_e32 v136, v134, v135
	v_lshl_add_u64 v[134:135], v[208:209], 4, s[48:49]
	v_readlane_b32 s48, v237, 58
	v_readlane_b32 s49, v237, 59
	s_lshl_b32 s48, s64, 2
	s_mov_b32 s31, s49
	v_writelane_b32 v237, s30, 58
	v_lshl_add_u64 v[134:135], v[134:135], 0, s[48:49]
	global_store_dword v[134:135], v136, off sc1
	v_writelane_b32 v237, s31, 59

; __device__ __forceinline__ float shx(float v, int o) { const int idx = (((int)otid() & 63) ^ o) << 2; return __builtin_bit_cast(float, __builtin_amdgcn_ds_bpermute(idx, __builtin_bit_cast(int, v))); }
; __device__ __forceinline__ void epi_all_run(const void* Pk_, int l, int s, const f32x4 (&acc)[2][2][4][2], const pg8::Unit& u, int wr, int wc, int fr, int fq) {
;     ...
;             for (int g = 0; g < 8; ++g) {
;                 const int ai = g >> 2, m = g & 3, row = row0 + ai * 128 + m * 16;
;                 if (g < 7) { const int rown = row0 + ((g + 1) >> 2) * 128 + ((g + 1) & 3) * 16;
; #pragma unroll
;                     for (int bj = 0; bj < 2; ++bj)
; #pragma unroll
;                         for (int n = 0; n < 2; ++n) bb[(g + 1) & 1][bj][n] = *(const f32x4*)(base + (size_t)rown * DM + col0 + bj * 128 + n * 4); }
;                 float ss = 0.f;
; #pragma unroll
;                 for (int bj = 0; bj < 2; ++bj)
; #pragma unroll
;                     for (int n = 0; n < 2; ++n) {
;                         const f32x4 h = bb[g & 1][bj][n] + gv[bj][n] * acc[ai][bj][m][n];
;                         *(f32x4*)(out + (size_t)row * DM + col0 + bj * 128 + n * 4) = h;
;                         ss += (h[0] * h[0] + h[1] * h[1]) + (h[2] * h[2] + h[3] * h[3]);
;                     }
;                 if (nsite < 3 * DEPTH) {
;                     ss += shx(ss, 16); ss += shx(ss, 32);
;                     if (fq == 0) __hip_atomic_store(slots + ((size_t)u.pn * M + row) * 4 + wc, ss, __ATOMIC_RELAXED, __HIP_MEMORY_SCOPE_AGENT);
;                 }
;             }
.LBB0_103:
	v_add_u32_e32 v208, 0x80, v184
	v_ashrrev_i32_e32 v209, 31, v208
	v_lshlrev_b64 v[212:213], 12, v[208:209]
	v_lshl_add_u64 v[138:139], v[206:207], 0, v[212:213]
	global_load_dwordx4 v[150:153], v[138:139], off offset:16
	global_load_dwordx4 v[162:165], v[138:139], off
	s_waitcnt lgkmcnt(0)
	global_load_dwordx4 v[134:137], v[138:139], off offset:528
	s_nop 0
	global_load_dwordx4 v[138:141], v[138:139], off offset:512
	v_lshl_add_u64 v[214:215], v[200:201], 0, v[214:215]
	s_waitcnt vmcnt(10)
	v_pk_fma_f32 v[80:81], v[80:81], v[202:203], v[168:169]
	v_pk_fma_f32 v[78:79], v[78:79], v[204:205], v[166:167]
	v_pk_fma_f32 v[76:77], v[76:77], v[198:199], v[160:161]
	v_pk_fma_f32 v[74:75], v[74:75], v[196:197], v[158:159]
	s_waitcnt vmcnt(8)
	v_pk_fma_f32 v[72:73], v[72:73], v[192:193], v[148:149]
	v_pk_fma_f32 v[70:71], v[70:71], v[194:195], v[146:147]
	v_pk_fma_f32 v[68:69], v[68:69], v[190:191], v[132:133]
	v_pk_fma_f32 v[66:67], v[66:67], v[188:189], v[130:131]
	s_and_b64 vcc, exec, s[4:5]
	global_store_dwordx4 v[214:215], v[78:81], off
	global_store_dwordx4 v[214:215], v[74:77], off offset:16
	global_store_dwordx4 v[214:215], v[70:73], off offset:512
	global_store_dwordx4 v[214:215], v[66:69], off offset:528
	s_cbranch_vccnz .LBB0_107
	v_pk_mul_f32 v[130:131], v[66:67], v[66:67]
	v_pk_fma_f32 v[130:131], v[68:69], v[68:69], v[130:131]
	v_pk_fma_f32 v[130:131], v[70:71], v[70:71], v[130:131]
	v_pk_fma_f32 v[130:131], v[72:73], v[72:73], v[130:131]
	v_pk_fma_f32 v[130:131], v[74:75], v[74:75], v[130:131]
	v_pk_fma_f32 v[130:131], v[76:77], v[76:77], v[130:131]
	v_pk_fma_f32 v[130:131], v[78:79], v[78:79], v[130:131]
	v_pk_fma_f32 v[130:131], v[80:81], v[80:81], v[130:131]
	v_add_f32_e32 v130, v130, v131
	v_mov_b32_e32 v131, v179
	v_lshlrev_b32_e32 v131, 2, v131
	v_bitop3_b32 v131, v131, 64, v220 bitop3:0x6c
	ds_bpermute_b32 v131, v131, v130
	s_waitcnt lgkmcnt(0)
	v_add_f32_e32 v130, v130, v131
	v_mov_b32_e32 v131, v179
	s_nop 0
	v_lshlrev_b32_e32 v131, 2, v131
	v_bitop3_b32 v131, v131, s33, v220 bitop3:0x6c
	ds_bpermute_b32 v131, v131, v130
	s_and_saveexec_b64 s[38:39], s[42:43]
	s_cbranch_execz .LBB0_106
	s_ashr_i32 s31, s30, 31
	s_lshl_b64 s[48:49], s[30:31], 18
	s_add_u32 s48, s20, s48
	s_addc_u32 s49, s46, s49
	s_waitcnt lgkmcnt(0)
	v_add_f32_e32 v132, v130, v131
	v_lshl_add_u64 v[130:131], v[210:211], 4, s[48:49]
	v_readlane_b32 s48, v237, 58
	v_readlane_b32 s49, v237, 59
	s_lshl_b32 s48, s64, 2
	s_mov_b32 s31, s49
	v_writelane_b32 v237, s30, 58
	v_lshl_add_u64 v[130:131], v[130:131], 0, s[48:49]
	global_store_dword v[130:131], v132, off sc1
	v_writelane_b32 v237, s31, 59

; __device__ __forceinline__ float shx(float v, int o) { const int idx = (((int)otid() & 63) ^ o) << 2; return __builtin_bit_cast(float, __builtin_amdgcn_ds_bpermute(idx, __builtin_bit_cast(int, v))); }
; __device__ __forceinline__ void epi_all_run(const void* Pk_, int l, int s, const f32x4 (&acc)[2][2][4][2], const pg8::Unit& u, int wr, int wc, int fr, int fq) {
;     ...
;             for (int g = 0; g < 8; ++g) {
;                 const int ai = g >> 2, m = g & 3, row = row0 + ai * 128 + m * 16;
;                 if (g < 7) { const int rown = row0 + ((g + 1) >> 2) * 128 + ((g + 1) & 3) * 16;
; #pragma unroll
;                     for (int bj = 0; bj < 2; ++bj)
; #pragma unroll
;                         for (int n = 0; n < 2; ++n) bb[(g + 1) & 1][bj][n] = *(const f32x4*)(base + (size_t)rown * DM + col0 + bj * 128 + n * 4); }
;                 float ss = 0.f;
; #pragma unroll
;                 for (int bj = 0; bj < 2; ++bj)
; #pragma unroll
;                     for (int n = 0; n < 2; ++n) {
;                         const f32x4 h = bb[g & 1][bj][n] + gv[bj][n] * acc[ai][bj][m][n];
;                         *(f32x4*)(out + (size_t)row * DM + col0 + bj * 128 + n * 4) = h;
;                         ss += (h[0] * h[0] + h[1] * h[1]) + (h[2] * h[2] + h[3] * h[3]);
;                     }
;                 if (nsite < 3 * DEPTH) {
;                     ss += shx(ss, 16); ss += shx(ss, 32);
;                     if (fq == 0) __hip_atomic_store(slots + ((size_t)u.pn * M + row) * 4 + wc, ss, __ATOMIC_RELAXED, __HIP_MEMORY_SCOPE_AGENT);
;                 }
;             }
.LBB0_107:
	v_or_b32_e32 v210, 16, v208
	v_ashrrev_i32_e32 v211, 31, v210
	v_lshlrev_b64 v[214:215], 12, v[210:211]
	v_lshl_add_u64 v[142:143], v[206:207], 0, v[214:215]
	global_load_dwordx4 v[154:157], v[142:143], off offset:16
	global_load_dwordx4 v[166:169], v[142:143], off
	s_waitcnt lgkmcnt(0)
	global_load_dwordx4 v[130:133], v[142:143], off offset:528
	s_nop 0
	global_load_dwordx4 v[142:145], v[142:143], off offset:512
	v_lshl_add_u64 v[158:159], v[200:201], 0, v[212:213]
	s_waitcnt vmcnt(10)
	v_pk_fma_f32 v[64:65], v[64:65], v[202:203], v[164:165]
	v_pk_fma_f32 v[62:63], v[62:63], v[204:205], v[162:163]
	v_pk_fma_f32 v[60:61], v[60:61], v[198:199], v[152:153]
	v_pk_fma_f32 v[58:59], v[58:59], v[196:197], v[150:151]
	s_waitcnt vmcnt(8)
	v_pk_fma_f32 v[56:57], v[56:57], v[192:193], v[140:141]
	v_pk_fma_f32 v[54:55], v[54:55], v[194:195], v[138:139]
	v_pk_fma_f32 v[52:53], v[52:53], v[190:191], v[136:137]
	v_pk_fma_f32 v[50:51], v[50:51], v[188:189], v[134:135]
	s_and_b64 vcc, exec, s[4:5]
	global_store_dwordx4 v[158:159], v[62:65], off
	global_store_dwordx4 v[158:159], v[58:61], off offset:16
	global_store_dwordx4 v[158:159], v[54:57], off offset:512
	global_store_dwordx4 v[158:159], v[50:53], off offset:528
	s_cbranch_vccnz .LBB0_111
	v_pk_mul_f32 v[134:135], v[50:51], v[50:51]
	v_pk_fma_f32 v[134:135], v[52:53], v[52:53], v[134:135]
	v_pk_fma_f32 v[134:135], v[54:55], v[54:55], v[134:135]
	v_pk_fma_f32 v[134:135], v[56:57], v[56:57], v[134:135]
	v_pk_fma_f32 v[134:135], v[58:59], v[58:59], v[134:135]
	v_pk_fma_f32 v[134:135], v[60:61], v[60:61], v[134:135]
	v_pk_fma_f32 v[134:135], v[62:63], v[62:63], v[134:135]
	v_pk_fma_f32 v[134:135], v[64:65], v[64:65], v[134:135]
	v_add_f32_e32 v134, v134, v135
	v_mov_b32_e32 v135, v179
	v_lshlrev_b32_e32 v135, 2, v135
	v_bitop3_b32 v135, v135, 64, v220 bitop3:0x6c
	ds_bpermute_b32 v135, v135, v134
	s_waitcnt lgkmcnt(0)
	v_add_f32_e32 v134, v134, v135
	v_mov_b32_e32 v135, v179
	s_nop 0
	v_lshlrev_b32_e32 v135, 2, v135
	v_bitop3_b32 v135, v135, s33, v220 bitop3:0x6c
	ds_bpermute_b32 v135, v135, v134
	s_and_saveexec_b64 s[38:39], s[42:43]
	s_cbranch_execz .LBB0_110
	s_ashr_i32 s31, s30, 31
	s_lshl_b64 s[48:49], s[30:31], 18
	s_add_u32 s48, s20, s48
	s_addc_u32 s49, s46, s49
	s_waitcnt lgkmcnt(0)
	v_add_f32_e32 v136, v134, v135
	v_lshl_add_u64 v[134:135], v[208:209], 4, s[48:49]
	v_readlane_b32 s48, v237, 58
	v_readlane_b32 s49, v237, 59
	s_lshl_b32 s48, s64, 2
	s_mov_b32 s31, s49
	v_writelane_b32 v237, s30, 58
	v_lshl_add_u64 v[134:135], v[134:135], 0, s[48:49]
	global_store_dword v[134:135], v136, off sc1
	v_writelane_b32 v237, s31, 59

; __device__ __forceinline__ float shx(float v, int o) { const int idx = (((int)otid() & 63) ^ o) << 2; return __builtin_bit_cast(float, __builtin_amdgcn_ds_bpermute(idx, __builtin_bit_cast(int, v))); }
; __device__ __forceinline__ void epi_all_run(const void* Pk_, int l, int s, const f32x4 (&acc)[2][2][4][2], const pg8::Unit& u, int wr, int wc, int fr, int fq) {
;     ...
;             for (int g = 0; g < 8; ++g) {
;                 const int ai = g >> 2, m = g & 3, row = row0 + ai * 128 + m * 16;
;                 if (g < 7) { const int rown = row0 + ((g + 1) >> 2) * 128 + ((g + 1) & 3) * 16;
; #pragma unroll
;                     for (int bj = 0; bj < 2; ++bj)
; #pragma unroll
;                         for (int n = 0; n < 2; ++n) bb[(g + 1) & 1][bj][n] = *(const f32x4*)(base + (size_t)rown * DM + col0 + bj * 128 + n * 4); }
;                 float ss = 0.f;
; #pragma unroll
;                 for (int bj = 0; bj < 2; ++bj)
; #pragma unroll
;                     for (int n = 0; n < 2; ++n) {
;                         const f32x4 h = bb[g & 1][bj][n] + gv[bj][n] * acc[ai][bj][m][n];
;                         *(f32x4*)(out + (size_t)row * DM + col0 + bj * 128 + n * 4) = h;
;                         ss += (h[0] * h[0] + h[1] * h[1]) + (h[2] * h[2] + h[3] * h[3]);
;                     }
;                 if (nsite < 3 * DEPTH) {
;                     ss += shx(ss, 16); ss += shx(ss, 32);
;                     if (fq == 0) __hip_atomic_store(slots + ((size_t)u.pn * M + row) * 4 + wc, ss, __ATOMIC_RELAXED, __HIP_MEMORY_SCOPE_AGENT);
;                 }
;             }
.LBB0_111:
	v_or_b32_e32 v162, 32, v208
	v_ashrrev_i32_e32 v163, 31, v162
	v_lshlrev_b64 v[212:213], 12, v[162:163]
	v_lshl_add_u64 v[138:139], v[206:207], 0, v[212:213]
	global_load_dwordx4 v[146:149], v[138:139], off offset:16
	global_load_dwordx4 v[158:161], v[138:139], off
	s_waitcnt lgkmcnt(0)
	global_load_dwordx4 v[134:137], v[138:139], off offset:528
	s_nop 0
	global_load_dwordx4 v[138:141], v[138:139], off offset:512
	v_lshl_add_u64 v[164:165], v[200:201], 0, v[214:215]
	s_waitcnt vmcnt(10)
	v_pk_fma_f32 v[48:49], v[48:49], v[202:203], v[168:169]
	v_pk_fma_f32 v[46:47], v[46:47], v[204:205], v[166:167]
	v_pk_fma_f32 v[44:45], v[44:45], v[198:199], v[156:157]
	v_pk_fma_f32 v[42:43], v[42:43], v[196:197], v[154:155]
	s_waitcnt vmcnt(8)
	v_pk_fma_f32 v[40:41], v[40:41], v[192:193], v[144:145]
	v_pk_fma_f32 v[38:39], v[38:39], v[194:195], v[142:143]
	v_pk_fma_f32 v[36:37], v[36:37], v[190:191], v[132:133]
	v_pk_fma_f32 v[34:35], v[34:35], v[188:189], v[130:131]
	s_and_b64 vcc, exec, s[4:5]
	global_store_dwordx4 v[164:165], v[46:49], off
	global_store_dwordx4 v[164:165], v[42:45], off offset:16
	global_store_dwordx4 v[164:165], v[38:41], off offset:512
	global_store_dwordx4 v[164:165], v[34:37], off offset:528
	s_cbranch_vccnz .LBB0_115
	v_pk_mul_f32 v[130:131], v[34:35], v[34:35]
	v_pk_fma_f32 v[130:131], v[36:37], v[36:37], v[130:131]
	v_pk_fma_f32 v[130:131], v[38:39], v[38:39], v[130:131]
	v_pk_fma_f32 v[130:131], v[40:41], v[40:41], v[130:131]
	v_pk_fma_f32 v[130:131], v[42:43], v[42:43], v[130:131]
	v_pk_fma_f32 v[130:131], v[44:45], v[44:45], v[130:131]
	v_pk_fma_f32 v[130:131], v[46:47], v[46:47], v[130:131]
	v_pk_fma_f32 v[130:131], v[48:49], v[48:49], v[130:131]
	v_add_f32_e32 v130, v130, v131
	v_mov_b32_e32 v131, v179
	v_lshlrev_b32_e32 v131, 2, v131
	v_bitop3_b32 v131, v131, 64, v220 bitop3:0x6c
	ds_bpermute_b32 v131, v131, v130
	s_waitcnt lgkmcnt(0)
	v_add_f32_e32 v130, v130, v131
	v_mov_b32_e32 v131, v179
	s_nop 0
	v_lshlrev_b32_e32 v131, 2, v131
	v_bitop3_b32 v131, v131, s33, v220 bitop3:0x6c
	ds_bpermute_b32 v131, v131, v130
	s_and_saveexec_b64 s[38:39], s[42:43]
	s_cbranch_execz .LBB0_114
	s_ashr_i32 s31, s30, 31
	s_lshl_b64 s[48:49], s[30:31], 18
	s_add_u32 s48, s20, s48
	s_addc_u32 s49, s46, s49
	s_waitcnt lgkmcnt(0)
	v_add_f32_e32 v132, v130, v131
	v_lshl_add_u64 v[130:131], v[210:211], 4, s[48:49]
	v_readlane_b32 s48, v237, 58
	v_readlane_b32 s49, v237, 59
	s_lshl_b32 s48, s64, 2
	s_mov_b32 s31, s49
	v_writelane_b32 v237, s30, 58
	v_lshl_add_u64 v[130:131], v[130:131], 0, s[48:49]
	global_store_dword v[130:131], v132, off sc1
	v_writelane_b32 v237, s31, 59

; __device__ __forceinline__ float shx(float v, int o) { const int idx = (((int)otid() & 63) ^ o) << 2; return __builtin_bit_cast(float, __builtin_amdgcn_ds_bpermute(idx, __builtin_bit_cast(int, v))); }
; __device__ __forceinline__ void epi_all_run(const void* Pk_, int l, int s, const f32x4 (&acc)[2][2][4][2], const pg8::Unit& u, int wr, int wc, int fr, int fq) {
;     ...
;             for (int g = 0; g < 8; ++g) {
;                 const int ai = g >> 2, m = g & 3, row = row0 + ai * 128 + m * 16;
;                 if (g < 7) { const int rown = row0 + ((g + 1) >> 2) * 128 + ((g + 1) & 3) * 16;
; #pragma unroll
;                     for (int bj = 0; bj < 2; ++bj)
; #pragma unroll
;                         for (int n = 0; n < 2; ++n) bb[(g + 1) & 1][bj][n] = *(const f32x4*)(base + (size_t)rown * DM + col0 + bj * 128 + n * 4); }
;                 float ss = 0.f;
; #pragma unroll
;                 for (int bj = 0; bj < 2; ++bj)
; #pragma unroll
;                     for (int n = 0; n < 2; ++n) {
;                         const f32x4 h = bb[g & 1][bj][n] + gv[bj][n] * acc[ai][bj][m][n];
;                         *(f32x4*)(out + (size_t)row * DM + col0 + bj * 128 + n * 4) = h;
;                         ss += (h[0] * h[0] + h[1] * h[1]) + (h[2] * h[2] + h[3] * h[3]);
;                     }
;                 if (nsite < 3 * DEPTH) {
;                     ss += shx(ss, 16); ss += shx(ss, 32);
;                     if (fq == 0) __hip_atomic_store(slots + ((size_t)u.pn * M + row) * 4 + wc, ss, __ATOMIC_RELAXED, __HIP_MEMORY_SCOPE_AGENT);
;                 }
;             }
.LBB0_115:
	v_or_b32_e32 v164, 48, v208
	v_ashrrev_i32_e32 v165, 31, v164
	v_lshlrev_b64 v[166:167], 12, v[164:165]
	v_lshl_add_u64 v[142:143], v[206:207], 0, v[166:167]
	global_load_dwordx4 v[150:153], v[142:143], off offset:16
	global_load_dwordx4 v[154:157], v[142:143], off
	s_waitcnt lgkmcnt(0)
	global_load_dwordx4 v[130:133], v[142:143], off offset:528
	s_nop 0
	global_load_dwordx4 v[142:145], v[142:143], off offset:512
	v_lshl_add_u64 v[168:169], v[200:201], 0, v[212:213]
	s_waitcnt vmcnt(10)
	v_pk_fma_f32 v[32:33], v[32:33], v[202:203], v[160:161]
	v_pk_fma_f32 v[30:31], v[30:31], v[204:205], v[158:159]
	v_pk_fma_f32 v[28:29], v[28:29], v[198:199], v[148:149]
	v_pk_fma_f32 v[26:27], v[26:27], v[196:197], v[146:147]
	s_waitcnt vmcnt(8)
	v_pk_fma_f32 v[24:25], v[24:25], v[192:193], v[140:141]
	v_pk_fma_f32 v[22:23], v[22:23], v[194:195], v[138:139]
	v_pk_fma_f32 v[20:21], v[20:21], v[190:191], v[136:137]
	v_pk_fma_f32 v[18:19], v[18:19], v[188:189], v[134:135]
	s_and_b64 vcc, exec, s[4:5]
	global_store_dwordx4 v[168:169], v[30:33], off
	global_store_dwordx4 v[168:169], v[26:29], off offset:16
	global_store_dwordx4 v[168:169], v[22:25], off offset:512
	global_store_dwordx4 v[168:169], v[18:21], off offset:528
	s_cbranch_vccnz .LBB0_119
	v_pk_mul_f32 v[134:135], v[18:19], v[18:19]
	v_pk_fma_f32 v[134:135], v[20:21], v[20:21], v[134:135]
	v_pk_fma_f32 v[134:135], v[22:23], v[22:23], v[134:135]
	v_pk_fma_f32 v[134:135], v[24:25], v[24:25], v[134:135]
	v_pk_fma_f32 v[134:135], v[26:27], v[26:27], v[134:135]
	v_pk_fma_f32 v[134:135], v[28:29], v[28:29], v[134:135]
	v_pk_fma_f32 v[134:135], v[30:31], v[30:31], v[134:135]
	v_pk_fma_f32 v[134:135], v[32:33], v[32:33], v[134:135]
	v_add_f32_e32 v134, v134, v135
	v_mov_b32_e32 v135, v179
	v_lshlrev_b32_e32 v135, 2, v135
	v_bitop3_b32 v135, v135, 64, v220 bitop3:0x6c
	ds_bpermute_b32 v135, v135, v134
	s_waitcnt lgkmcnt(0)
	v_add_f32_e32 v134, v134, v135
	v_mov_b32_e32 v135, v179
	s_nop 0
	v_lshlrev_b32_e32 v135, 2, v135
	v_bitop3_b32 v135, v135, s33, v220 bitop3:0x6c
	ds_bpermute_b32 v135, v135, v134
	s_and_saveexec_b64 s[38:39], s[42:43]
	s_cbranch_execz .LBB0_118
	s_ashr_i32 s31, s30, 31
	s_lshl_b64 s[48:49], s[30:31], 18
	s_add_u32 s48, s20, s48
	s_addc_u32 s49, s46, s49
	s_waitcnt lgkmcnt(0)
	v_add_f32_e32 v136, v134, v135
	v_lshl_add_u64 v[134:135], v[162:163], 4, s[48:49]
	v_readlane_b32 s48, v237, 58
	v_readlane_b32 s49, v237, 59
	s_lshl_b32 s48, s64, 2
	s_mov_b32 s31, s49
	v_writelane_b32 v237, s30, 58
	v_lshl_add_u64 v[134:135], v[134:135], 0, s[48:49]
	global_store_dword v[134:135], v136, off sc1
	v_writelane_b32 v237, s31, 59

; __device__ __forceinline__ float shx(float v, int o) { const int idx = (((int)otid() & 63) ^ o) << 2; return __builtin_bit_cast(float, __builtin_amdgcn_ds_bpermute(idx, __builtin_bit_cast(int, v))); }
; __device__ __forceinline__ void epi_all_run(const void* Pk_, int l, int s, const f32x4 (&acc)[2][2][4][2], const pg8::Unit& u, int wr, int wc, int fr, int fq) {
;     ...
;             for (int g = 0; g < 8; ++g) {
;                 const int ai = g >> 2, m = g & 3, row = row0 + ai * 128 + m * 16;
;                 if (g < 7) { const int rown = row0 + ((g + 1) >> 2) * 128 + ((g + 1) & 3) * 16;
; #pragma unroll
;                     for (int bj = 0; bj < 2; ++bj)
; #pragma unroll
;                         for (int n = 0; n < 2; ++n) bb[(g + 1) & 1][bj][n] = *(const f32x4*)(base + (size_t)rown * DM + col0 + bj * 128 + n * 4); }
;                 float ss = 0.f;
; #pragma unroll
;                 for (int bj = 0; bj < 2; ++bj)
; #pragma unroll
;                     for (int n = 0; n < 2; ++n) {
;                         const f32x4 h = bb[g & 1][bj][n] + gv[bj][n] * acc[ai][bj][m][n];
;                         *(f32x4*)(out + (size_t)row * DM + col0 + bj * 128 + n * 4) = h;
;                         ss += (h[0] * h[0] + h[1] * h[1]) + (h[2] * h[2] + h[3] * h[3]);
;                     }
;                 if (nsite < 3 * DEPTH) {
;                     ss += shx(ss, 16); ss += shx(ss, 32);
;                     if (fq == 0) __hip_atomic_store(slots + ((size_t)u.pn * M + row) * 4 + wc, ss, __ATOMIC_RELAXED, __HIP_MEMORY_SCOPE_AGENT);
;                 }
;             }
.LBB0_119:
	v_lshl_add_u64 v[146:147], v[200:201], 0, v[166:167]
	s_waitcnt vmcnt(6)
	v_pk_fma_f32 v[16:17], v[16:17], v[202:203], v[156:157]
	s_waitcnt lgkmcnt(0)
	v_pk_fma_f32 v[14:15], v[14:15], v[204:205], v[154:155]
	v_pk_fma_f32 v[12:13], v[12:13], v[198:199], v[152:153]
	v_pk_fma_f32 v[10:11], v[10:11], v[196:197], v[150:151]
	s_waitcnt vmcnt(4)
	v_pk_fma_f32 v[8:9], v[8:9], v[192:193], v[144:145]
	v_pk_fma_f32 v[6:7], v[6:7], v[194:195], v[142:143]
	v_pk_fma_f32 v[4:5], v[4:5], v[190:191], v[132:133]
	v_pk_fma_f32 v[2:3], v[2:3], v[188:189], v[130:131]
	s_and_b64 vcc, exec, s[4:5]
	global_store_dwordx4 v[146:147], v[14:17], off
	global_store_dwordx4 v[146:147], v[10:13], off offset:16
	global_store_dwordx4 v[146:147], v[6:9], off offset:512
	global_store_dwordx4 v[146:147], v[2:5], off offset:528
	s_cbranch_vccnz .LBB0_123
	v_pk_mul_f32 v[130:131], v[2:3], v[2:3]
	v_pk_fma_f32 v[130:131], v[4:5], v[4:5], v[130:131]
	v_pk_fma_f32 v[130:131], v[6:7], v[6:7], v[130:131]
	v_pk_fma_f32 v[130:131], v[8:9], v[8:9], v[130:131]
	v_pk_fma_f32 v[130:131], v[10:11], v[10:11], v[130:131]
	v_pk_fma_f32 v[130:131], v[12:13], v[12:13], v[130:131]
	v_pk_fma_f32 v[130:131], v[14:15], v[14:15], v[130:131]
	v_pk_fma_f32 v[130:131], v[16:17], v[16:17], v[130:131]
	v_add_f32_e32 v130, v130, v131
	v_mov_b32_e32 v131, v179
	v_lshlrev_b32_e32 v131, 2, v131
	v_bitop3_b32 v131, v131, 64, v220 bitop3:0x6c
	ds_bpermute_b32 v131, v131, v130
	s_waitcnt lgkmcnt(0)
	v_add_f32_e32 v130, v130, v131
	v_mov_b32_e32 v131, v179
	s_nop 0
	v_lshlrev_b32_e32 v131, 2, v131
	v_bitop3_b32 v131, v131, s33, v220 bitop3:0x6c
	ds_bpermute_b32 v131, v131, v130
	s_and_saveexec_b64 s[4:5], s[42:43]
	s_cbranch_execz .LBB0_122
	s_ashr_i32 s31, s30, 31
	s_lshl_b64 s[38:39], s[30:31], 18
	s_add_u32 s38, s20, s38
	s_addc_u32 s39, s46, s39
	s_waitcnt lgkmcnt(0)
	v_add_f32_e32 v132, v130, v131
	v_lshl_add_u64 v[130:131], v[164:165], 4, s[38:39]
	v_readlane_b32 s38, v237, 58
	v_readlane_b32 s39, v237, 59
	s_lshl_b32 s38, s64, 2
	s_mov_b32 s31, s39
	v_writelane_b32 v237, s30, 58
	v_lshl_add_u64 v[130:131], v[130:131], 0, s[38:39]
	global_store_dword v[130:131], v132, off sc1
	v_writelane_b32 v237, s31, 59
